# S5 post start-state loop rotated: first round of block-total loads issued before the initial parameter wait (one load latency per item overlapped)
# speedup vs baseline: 1.0011x; 1.0011x over previous
; #define GAS __attribute__((address_space(1)))
; #define LAS __attribute__((address_space(3)))
; #define SB() __builtin_amdgcn_sched_barrier(0)
; template <bool POST>
; DI void s5_phase(const Frame& F, const CAS Args& a, int l, int first, int stride) {
;     ...
;         const int g = it >> 4, ib = it & 15;
;         const unsigned char* tb = F.ws + WS_S5TA + ((size_t)l * S5G + g) * S5T_SIZE;
;         float* TOT = (float*)(F.ws + WS_S5X) + (size_t)(g * 16) * 128;
;         LAS float* const TW = (LAS float*)(F.lds + S5_TW) + par * 8 * 128;
;         LAS float* const X0 = (LAS float*)(F.lds + S5_X0) + par * 128;
;         const int sb = 128 * ib + 16 * w + n;
;         const unsigned char* zb = F.ws + WS_ZS5 + ((size_t)g * M + 8 * (128 * ib + 16 * w)) * 32;
;         unsigned lzu = (unsigned)((8 * n + (kg >> 1)) * 32 + (kg & 1) * 16);
;         unsigned lzo = (unsigned)(8 * n * 32 + 8 * kg);
;         unsigned ltab = (unsigned)lane * 16u;
;         unsigned lyo = (unsigned)(8 * n * S5W + 4 * kg) * 2u;
;         asm volatile("" : "+v"(lzu), "+v"(lzo), "+v"(ltab), "+v"(lyo));
;         bf16x8 uf[4];
; #pragma unroll
;         for (int ks = 0; ks < 4; ++ks) uf[ks] = LDU(bf16x8, zb + 64 * ks, lzu);
;         f32x4 Ar[4], Ai[4];
; #pragma unroll
;         for (int m = 0; m < 4; ++m) { Ar[m] = *(const GAS f32x4*)((const float*)(tb + S5T_L8) + 16 * m + 4 * kg); Ai[m] = *(const GAS f32x4*)((const float*)(tb + S5T_L8) + 64 + 16 * m + 4 * kg); }
;         if (POST && w == 0) { const int p = lane; const float lnr = ((const GAS float*)(tb + S5T_LN))[p], lni = ((const GAS float*)(tb + S5T_LN))[64 + p];
;             float xr = 0.f, xi = 0.f;
;             for (int q0 = 0; q0 < ib; q0 += 4) { float tr[4], ti[4];
; #pragma unroll
;                 for (int u = 0; u < 4; ++u) { const int q = (q0 + u < ib) ? q0 + u : q0; tr[u] = TOT[q * 128 + p]; ti[u] = TOT[q * 128 + 64 + p]; }
;                 SB();
; #pragma unroll
;                 for (int u = 0; u < 4; ++u) if (q0 + u < ib) { const float t0 = lnr * xr - lni * xi + tr[u], t1 = lnr * xi + lni * xr + ti[u]; xr = t0; xi = t1; }
;                 SB(); }
;             X0[p] = xr; X0[64 + p] = xi; }
.LBB0_789:
	s_ashr_i32 s6, s20, 4
	s_and_b32 s0, s20, 15
	s_ashr_i32 s7, s6, 31
	s_mul_i32 s1, s71, 48
	s_add_u32 s1, s1, s6
	s_mul_hi_u32 s8, s71, 48
	s_addc_u32 s8, s8, s7
	s_mul_i32 s8, s8, 0x1a400
	s_mul_hi_u32 s9, s1, 0x1a400
	s_add_i32 s9, s9, s8
	s_mul_i32 s1, s1, 0x1a400
	s_add_u32 s18, s27, s1
	s_addc_u32 s19, s30, s9
	s_lshl_b32 s1, s36, 12
	s_add_i32 s37, s1, 0
	s_lshl_b32 s1, s0, 10
	v_readlane_b32 s8, v253, 51
	s_add_i32 s10, s1, s8
	s_and_b32 s12, s20, -16
	s_ashr_i32 s11, s10, 31
	s_ashr_i32 s13, s12, 31
	s_lshl_b64 s[6:7], s[6:7], 19
	s_lshl_b64 s[8:9], s[10:11], 5
	s_add_u32 s1, s31, s6
	s_addc_u32 s6, s33, s7
	s_add_u32 s14, s1, s8
	v_mov_b32_e32 v89, v185
	s_addc_u32 s15, s6, s9
	v_lshl_add_u64 v[0:1], s[18:19], 0, v[88:89]
	s_mov_b64 s[6:7], 0x18000
	v_lshl_add_u64 v[2:3], v[0:1], 0, s[6:7]
	s_mov_b64 s[6:7], 0x18100
	s_mov_b32 s1, 0x18000
	v_mov_b32_e32 v94, v81
	v_mov_b32_e32 v48, v135
	v_mov_b32_e32 v93, v134
	v_mov_b32_e32 v92, v136
	v_lshl_add_u64 v[4:5], v[0:1], 0, s[6:7]
	v_add_co_u32_e32 v0, vcc, s1, v0
	global_load_dwordx4 v[32:35], v94, s[14:15]
	global_load_dwordx4 v[36:39], v94, s[14:15] offset:64
	global_load_dwordx4 v[40:43], v94, s[14:15] offset:128
	global_load_dwordx4 v[44:47], v94, s[14:15] offset:192
	v_addc_co_u32_e32 v1, vcc, 0, v1, vcc
	global_load_dwordx4 v[28:31], v[0:1], off
	global_load_dwordx4 v[24:27], v[0:1], off offset:256
	global_load_dwordx4 v[16:19], v[2:3], off offset:64
	global_load_dwordx4 v[8:11], v[2:3], off offset:128
	global_load_dwordx4 v[20:23], v[4:5], off offset:64
	s_nop 0
	global_load_dwordx4 v[0:3], v[2:3], off offset:192
	s_nop 0
	global_load_dwordx4 v[12:15], v[4:5], off offset:128
	s_nop 0
	global_load_dwordx4 v[4:7], v[4:5], off offset:192
	v_readlane_b32 s6, v252, 5
	s_mul_i32 s1, s36, 0xfffff200
	v_readlane_b32 s7, v252, 6
	s_and_b64 vcc, exec, s[6:7]
	s_add_i32 s11, s37, s1
	s_movk_i32 s1, 0x7000
	s_cbranch_vccnz .LBB0_796
	s_cmp_eq_u32 s0, 0
	s_cbranch_scc1 .LBB0_794
	s_add_u32 s6, s18, 0x18200
	s_addc_u32 s7, s19, 0
	global_load_dword v50, v137, s[6:7]
	global_load_dword v52, v138, s[6:7]
	s_lshl_b64 s[6:7], s[12:13], 9
	v_lshl_add_u64 v[54:55], v[84:85], 0, s[6:7]
	s_lshl_b64 s[6:7], s[12:13], 9
	s_add_u32 s22, s34, s6
	v_mov_b32_e32 v61, 0
	s_addc_u32 s23, s35, s7
	s_mov_b32 s1, 0
	v_mov_b32_e32 v60, v61
	s_add_i32 s8, s1, 1
	s_cmp_lt_u32 s8, s0
	s_cselect_b64 vcc, -1, 0
	s_and_b64 s[6:7], vcc, exec
	s_cselect_b32 s6, s8, s1
	s_add_i32 s38, s1, 2
	s_cmp_lt_u32 s38, s0
	v_lshl_or_b32 v184, s6, 7, v128
	s_cselect_b64 s[6:7], -1, 0
	s_and_b64 s[8:9], s[6:7], exec
	s_cselect_b32 s8, s38, s1
	s_add_i32 s40, s1, 3
	s_cmp_lt_u32 s40, s0
	v_lshl_add_u64 v[64:65], v[184:185], 2, s[22:23]
	v_lshl_or_b32 v184, s8, 7, v128
	s_cselect_b64 s[8:9], -1, 0
	s_and_b64 s[38:39], s[8:9], exec
	s_cselect_b32 s38, s40, s1
	global_load_dword v63, v[54:55], off offset:-256
	global_load_dword v62, v[54:55], off
	global_load_dword v67, v[64:65], off
	global_load_dword v66, v[64:65], off offset:256
	v_lshl_add_u64 v[64:65], v[184:185], 2, s[22:23]
	v_lshl_or_b32 v184, s38, 7, v128
	global_load_dword v69, v[64:65], off
	global_load_dword v68, v[64:65], off offset:256
	v_lshl_add_u64 v[64:65], v[184:185], 2, s[22:23]
	global_load_dword v49, v[64:65], off
	global_load_dword v72, v[64:65], off offset:256
	s_waitcnt vmcnt(9)
	v_mov_b32_e32 v51, v50
	s_waitcnt vmcnt(8)
	v_mov_b32_e32 v53, v52
	v_mov_b32_e32 v56, v50
	v_mov_b32_e32 v57, v52
	v_mov_b32_e32 v58, v52
	v_mov_b32_e32 v59, v50
.LBB0_792:
	v_pk_mul_f32 v[64:65], v[52:53], v[60:61]
	s_nop 0
	v_pk_fma_f32 v[70:71], v[50:51], v[60:61], v[64:65] op_sel:[0,0,1] op_sel_hi:[1,1,0]
	v_pk_fma_f32 v[60:61], v[50:51], v[60:61], v[64:65] op_sel:[0,0,1] op_sel_hi:[1,1,0] neg_lo:[0,0,1] neg_hi:[0,0,1]
	s_nop 0
	v_mov_b32_e32 v71, v61
	s_waitcnt vmcnt(6)
	v_pk_add_f32 v[60:61], v[70:71], v[62:63]
	s_nop 0
	v_pk_mul_f32 v[62:63], v[52:53], v[60:61]
	s_nop 0
	v_pk_fma_f32 v[64:65], v[50:51], v[60:61], v[62:63] op_sel:[0,0,1] op_sel_hi:[1,1,0]
	v_pk_fma_f32 v[62:63], v[50:51], v[60:61], v[62:63] op_sel:[0,0,1] op_sel_hi:[1,1,0] neg_lo:[0,0,1] neg_hi:[0,0,1]
	s_nop 0
	v_mov_b32_e32 v65, v63
	s_waitcnt vmcnt(4)
	v_pk_add_f32 v[62:63], v[66:67], v[64:65]
	s_nop 0
	v_cndmask_b32_e32 v61, v61, v63, vcc
	v_cndmask_b32_e32 v60, v60, v62, vcc
	v_pk_mul_f32 v[62:63], v[52:53], v[60:61]
	s_nop 0
	v_pk_fma_f32 v[64:65], v[50:51], v[60:61], v[62:63] op_sel:[0,0,1] op_sel_hi:[1,1,0]
	v_pk_fma_f32 v[62:63], v[50:51], v[60:61], v[62:63] op_sel:[0,0,1] op_sel_hi:[1,1,0] neg_lo:[0,0,1] neg_hi:[0,0,1]
	s_nop 0
	v_mov_b32_e32 v65, v63
	s_waitcnt vmcnt(2)
	v_pk_add_f32 v[62:63], v[68:69], v[64:65]
	s_nop 0
	v_cndmask_b32_e64 v61, v61, v63, s[6:7]
	v_cndmask_b32_e64 v60, v60, v62, s[6:7]
	v_pk_mul_f32 v[62:63], v[56:57], v[60:61]
	s_nop 0
	v_add_f32_e32 v64, v62, v63
	v_pk_mul_f32 v[62:63], v[58:59], v[60:61]
	s_nop 0
	v_sub_f32_e32 v62, v63, v62
	s_waitcnt vmcnt(1)
	v_add_f32_e32 v49, v49, v62
	s_waitcnt vmcnt(0)
	v_add_f32_e32 v62, v72, v64
	v_cndmask_b32_e64 v60, v60, v62, s[8:9]
	v_cndmask_b32_e64 v61, v61, v49, s[8:9]
	s_add_i32 s1, s1, 4
	s_mov_b64 s[6:7], 0x800
	s_cmp_ge_u32 s1, s0
	v_lshl_add_u64 v[54:55], v[54:55], 0, s[6:7]
	s_cbranch_scc1 .Ls5x_done
	s_add_i32 s8, s1, 1
	s_cmp_lt_u32 s8, s0
	s_cselect_b64 vcc, -1, 0
	s_and_b64 s[6:7], vcc, exec
	s_cselect_b32 s6, s8, s1
	s_add_i32 s38, s1, 2
	s_cmp_lt_u32 s38, s0
	v_lshl_or_b32 v184, s6, 7, v128
	s_cselect_b64 s[6:7], -1, 0
	s_and_b64 s[8:9], s[6:7], exec
	s_cselect_b32 s8, s38, s1
	s_add_i32 s40, s1, 3
	s_cmp_lt_u32 s40, s0
	v_lshl_add_u64 v[64:65], v[184:185], 2, s[22:23]
	v_lshl_or_b32 v184, s8, 7, v128
	s_cselect_b64 s[8:9], -1, 0
	s_and_b64 s[38:39], s[8:9], exec
	s_cselect_b32 s38, s40, s1
	global_load_dword v63, v[54:55], off offset:-256
	global_load_dword v62, v[54:55], off
	global_load_dword v67, v[64:65], off
	global_load_dword v66, v[64:65], off offset:256
	v_lshl_add_u64 v[64:65], v[184:185], 2, s[22:23]
	v_lshl_or_b32 v184, s38, 7, v128
	global_load_dword v69, v[64:65], off
	global_load_dword v68, v[64:65], off offset:256
	v_lshl_add_u64 v[64:65], v[184:185], 2, s[22:23]
	global_load_dword v49, v[64:65], off
	global_load_dword v72, v[64:65], off offset:256
	s_branch .LBB0_792
.Ls5x_done:
	s_movk_i32 s1, 0x7000
	s_branch .LBB0_795
